# indexer keys stored by the prep phase in MFMA operand order per 16-key group: score-loop fragment requests cover 8 full cache lines instead of 16 half lines
# speedup vs baseline: 1.0022x; 1.0022x over previous
; __device__ __forceinline__ void prep_unit(const Args& a, LAS unsigned char* lds, int b, int kt, int tid) {
;     const GAS bf16* z = (const GAS bf16*)(a.ws + WS_Z);
;     LAS bf16* tT = (LAS bf16*)lds;
;     const int key = tid >> 3, ch = tid & 7; const size_t row = (size_t)b * SEQ + kt * 64 + key;
;     const u32x4 d0 = *(const GAS u32x4*)(z + row * ZW + ZDC + 16 * ch), d1 = *(const GAS u32x4*)(z + row * ZW + ZDC + 16 * ch + 8);
;     const u32x4 k0 = *(const GAS u32x4*)(z + row * ZW + ZIK + 8 * ch);
;     float v[16]; float ss = 0.f;
; #pragma unroll
;     for (int i = 0; i < 4; ++i) { v[2 * i] = bflo(d0[i]); v[2 * i + 1] = bfhi(d0[i]); v[8 + 2 * i] = bflo(d1[i]); v[8 + 2 * i + 1] = bfhi(d1[i]); }
; #pragma unroll
;     for (int i = 0; i < 16; ++i) ss += v[i] * v[i];
;     ss += __shfl_xor(ss, 1); ss += __shfl_xor(ss, 2); ss += __shfl_xor(ss, 4);
;     const float r = rsqrtf(ss * (1.f / 128.f) + EPS);
;     unsigned short o[16];
;     u32x4 w0, w1;
; #pragma unroll
;     for (int i = 0; i < 4; ++i) { w0[i] = pk2(v[2 * i] * r, v[2 * i + 1] * r); w1[i] = pk2(v[8 + 2 * i] * r, v[8 + 2 * i + 1] * r);
;         o[2 * i] = (unsigned short)(w0[i] & 0xffffu); o[2 * i + 1] = (unsigned short)(w0[i] >> 16); o[8 + 2 * i] = (unsigned short)(w1[i] & 0xffffu); o[8 + 2 * i + 1] = (unsigned short)(w1[i] >> 16); }
;     GAS bf16* ckv = (GAS bf16*)(a.ws + WS_CKV);
;     *(GAS u32x4*)(ckv + row * 128 + 16 * ch) = w0; *(GAS u32x4*)(ckv + row * 128 + 16 * ch + 8) = w1;
; #pragma unroll
;     for (int i = 0; i < 16; ++i) tT[(16 * ch + i) * 72 + key] = o[i];
;     float kv[8]; float s2 = 0.f;
; #pragma unroll
;     for (int i = 0; i < 4; ++i) { kv[2 * i] = bflo(k0[i]); kv[2 * i + 1] = bfhi(k0[i]); }
; #pragma unroll
;     for (int i = 0; i < 8; ++i) s2 += kv[i] * kv[i];
;     s2 += __shfl_xor(s2, 1); s2 += __shfl_xor(s2, 2); s2 += __shfl_xor(s2, 4);
;     const float r2 = rsqrtf(s2 * (1.f / 64.f) + EPS);
;     u32x4 wk;
; #pragma unroll
;     for (int i = 0; i < 4; ++i) wk[i] = pk2(kv[2 * i] * r2, kv[2 * i + 1] * r2);
;     *(GAS u32x4*)((GAS bf16*)(a.ws + WS_IKN) + row * 64 + 8 * ch) = wk;
;     __syncthreads();
;     const int c = tid >> 2, q4 = tid & 3;
;     const u32x4 t0 = *(const LAS u32x4*)(tT + c * 72 + 16 * q4), t1 = *(const LAS u32x4*)(tT + c * 72 + 16 * q4 + 8);
;     GAS bf16* dst = (GAS bf16*)(a.ws + WS_CKVT) + ((size_t)b * 128 + c) * SEQ + kt * 64 + 16 * q4;
.LBB0_927:
	s_or_b64 exec, exec, s[0:1]
	v_readlane_b32 s0, v254, 7
	v_readlane_b32 s1, v254, 8
	s_and_b64 vcc, exec, s[0:1]
	s_waitcnt lgkmcnt(0)
	s_barrier
	s_cbranch_vccnz .LBB0_930
	v_mbcnt_hi_u32_b32 v2, -1, v225
	v_and_b32_e32 v4, 64, v2
	v_xor_b32_e32 v3, 1, v2
	v_add_u32_e32 v4, 64, v4
	v_cmp_lt_i32_e32 vcc, v3, v4
	v_mov_b32_e32 v1, 0
	v_lshlrev_b32_e32 v8, 4, v252
	v_cndmask_b32_e32 v3, v2, v3, vcc
	v_lshlrev_b32_e32 v18, 2, v3
	v_xor_b32_e32 v3, 2, v2
	v_cmp_lt_i32_e32 vcc, v3, v4
	v_lshrrev_b32_e32 v6, 2, v252
	v_and_b32_e32 v16, 48, v8
	v_cndmask_b32_e32 v3, v2, v3, vcc
	v_lshlrev_b32_e32 v19, 2, v3
	v_xor_b32_e32 v3, 4, v2
	v_cmp_lt_i32_e32 vcc, v3, v4
	v_lshlrev_b32_e32 v0, 4, v226
	s_mov_b64 s[4:5], 0x1b400000
	v_cndmask_b32_e32 v2, v2, v3, vcc
	v_lshlrev_b32_e32 v20, 2, v2
	v_lshlrev_b32_e32 v2, 5, v226
	v_mov_b32_e32 v3, v1
	v_lshl_add_u64 v[2:3], s[80:81], 0, v[2:3]
	v_mul_u32_u24_e32 v7, 0x90, v6
	v_lshlrev_b32_e32 v8, 1, v16
	v_lshl_add_u64 v[2:3], v[2:3], 0, s[4:5]
	v_lshlrev_b32_e32 v4, 8, v226
	v_mov_b32_e32 v5, v1
	v_lshl_add_u64 v[4:5], s[80:81], 0, v[4:5]
	s_mov_b64 s[4:5], 0x1c400000
	v_add3_u32 v21, 0, v7, v8
	v_lshlrev_b32_e32 v6, 12, v6
	v_mov_b32_e32 v7, v1
	s_add_u32 s2, s80, 0x8400000
	v_lshrrev_b32_e32 v15, 3, v252
	v_lshl_add_u64 v[4:5], v[4:5], 0, s[4:5]
	v_lshl_add_u64 v[6:7], s[80:81], 0, v[6:7]
	s_mov_b64 s[4:5], 0x1bc00000
	s_addc_u32 s3, s81, 0
	v_lshlrev_b32_e32 v12, 3, v226
	v_lshl_add_u32 v17, v15, 1, 0
	v_mul_u32_u24_e32 v22, 0x900, v226
	v_lshl_add_u64 v[6:7], v[6:7], 0, s[4:5]
	s_mov_b32 s4, 0x3c800000
	s_mov_b32 s1, 0
	s_lshl_b32 s8, s89, 6
	s_lshl_b32 s9, s84, 6
	s_movk_i32 s10, 0x1e00
	v_mov_b64_e32 v[8:9], s[2:3]
	v_lshlrev_b32_e32 v10, 1, v0
	v_mov_b32_e32 v11, v1
	s_mov_b64 s[2:3], 0x1800
	s_movk_i32 s11, 0x1000
	v_lshlrev_b32_e32 v12, 1, v12
	v_mov_b32_e32 v13, v1
	s_brev_b32 s5, 60
	v_mov_b32_e32 v14, 0x358637bd
	s_mov_b32 s12, 0x800000
	v_add_u32_e32 v22, v17, v22
	v_lshlrev_b32_e32 v16, 1, v16
	v_mov_b32_e32 v17, v1
	s_mov_b32 s13, s89
; __device__ __forceinline__ void prep_unit(const Args& a, LAS unsigned char* lds, int b, int kt, int tid) {
;     const GAS bf16* z = (const GAS bf16*)(a.ws + WS_Z);
;     LAS bf16* tT = (LAS bf16*)lds;
;     const int key = tid >> 3, ch = tid & 7; const size_t row = (size_t)b * SEQ + kt * 64 + key;
;     const u32x4 d0 = *(const GAS u32x4*)(z + row * ZW + ZDC + 16 * ch), d1 = *(const GAS u32x4*)(z + row * ZW + ZDC + 16 * ch + 8);
;     const u32x4 k0 = *(const GAS u32x4*)(z + row * ZW + ZIK + 8 * ch);
;     float v[16]; float ss = 0.f;
; #pragma unroll
;     for (int i = 0; i < 4; ++i) { v[2 * i] = bflo(d0[i]); v[2 * i + 1] = bfhi(d0[i]); v[8 + 2 * i] = bflo(d1[i]); v[8 + 2 * i + 1] = bfhi(d1[i]); }
; #pragma unroll
;     for (int i = 0; i < 16; ++i) ss += v[i] * v[i];
;     ss += __shfl_xor(ss, 1); ss += __shfl_xor(ss, 2); ss += __shfl_xor(ss, 4);
;     const float r = rsqrtf(ss * (1.f / 128.f) + EPS);
;     unsigned short o[16];
;     u32x4 w0, w1;
; #pragma unroll
;     for (int i = 0; i < 4; ++i) { w0[i] = pk2(v[2 * i] * r, v[2 * i + 1] * r); w1[i] = pk2(v[8 + 2 * i] * r, v[8 + 2 * i + 1] * r);
;         o[2 * i] = (unsigned short)(w0[i] & 0xffffu); o[2 * i + 1] = (unsigned short)(w0[i] >> 16); o[8 + 2 * i] = (unsigned short)(w1[i] & 0xffffu); o[8 + 2 * i + 1] = (unsigned short)(w1[i] >> 16); }
;     GAS bf16* ckv = (GAS bf16*)(a.ws + WS_CKV);
;     *(GAS u32x4*)(ckv + row * 128 + 16 * ch) = w0; *(GAS u32x4*)(ckv + row * 128 + 16 * ch + 8) = w1;
; #pragma unroll
;     for (int i = 0; i < 16; ++i) tT[(16 * ch + i) * 72 + key] = o[i];
;     float kv[8]; float s2 = 0.f;
; #pragma unroll
;     for (int i = 0; i < 4; ++i) { kv[2 * i] = bflo(k0[i]); kv[2 * i + 1] = bfhi(k0[i]); }
; #pragma unroll
;     for (int i = 0; i < 8; ++i) s2 += kv[i] * kv[i];
;     s2 += __shfl_xor(s2, 1); s2 += __shfl_xor(s2, 2); s2 += __shfl_xor(s2, 4);
;     const float r2 = rsqrtf(s2 * (1.f / 64.f) + EPS);
;     u32x4 wk;
; #pragma unroll
;     for (int i = 0; i < 4; ++i) wk[i] = pk2(kv[2 * i] * r2, kv[2 * i + 1] * r2);
;     *(GAS u32x4*)((GAS bf16*)(a.ws + WS_IKN) + row * 64 + 8 * ch) = wk;
;     __syncthreads();
;     const int c = tid >> 2, q4 = tid & 3;
;     const u32x4 t0 = *(const LAS u32x4*)(tT + c * 72 + 16 * q4), t1 = *(const LAS u32x4*)(tT + c * 72 + 16 * q4 + 8);
;     GAS bf16* dst = (GAS bf16*)(a.ws + WS_CKVT) + ((size_t)b * 128 + c) * SEQ + kt * 64 + 16 * q4;
.LBB0_929:
	s_bfe_u32 s0, s13, 0x40005
	s_and_b32 s6, s8, 0x7c0
	s_lshl_b32 s7, s0, 11
	s_lshl_b32 s0, s0, 19
	s_or_b32 s7, s7, s6
	v_lshl_add_u64 v[24:25], v[6:7], 0, s[0:1]
	s_lshl_b32 s0, s6, 1
	v_add_u32_e32 v23, s7, v15
	v_lshl_add_u64 v[24:25], v[24:25], 0, s[0:1]
	v_mad_u64_u32 v[26:27], s[6:7], v23, s10, v[8:9]
	v_lshl_add_u64 v[36:37], v[24:25], 0, v[16:17]
	v_lshl_add_u64 v[24:25], v[26:27], 0, v[10:11]
	v_add_co_u32_e32 v40, vcc, 0x1000, v24
	v_lshl_add_u64 v[32:33], v[26:27], 0, v[12:13]
	v_lshl_add_u64 v[34:35], v[24:25], 0, s[2:3]
	v_addc_co_u32_e32 v41, vcc, 0, v25, vcc
	v_add_co_u32_e32 v32, vcc, s11, v32
	global_load_dwordx4 v[24:27], v[34:35], off offset:16
	global_load_dwordx4 v[28:31], v[40:41], off offset:2048
	v_addc_co_u32_e32 v33, vcc, 0, v33, vcc
	global_load_dwordx4 v[32:35], v[32:33], off offset:3328
	v_lshlrev_b32_e32 v0, 8, v23
	v_lshl_add_u64 v[38:39], v[2:3], 0, v[0:1]
	v_lshlrev_b32_e32 v0, 7, v23
	v_bfe_u32 v42, v23, 0, 4
	v_and_b32_e32 v0, 0xfffff800, v0
	v_lshl_or_b32 v0, v42, 4, v0
	v_lshl_add_u64 v[42:43], v[4:5], 0, v[0:1]
	s_add_i32 s13, s13, s84
	s_add_i32 s8, s8, s9
	s_cmpk_gt_i32 s13, 0x1ff
	s_waitcnt vmcnt(0)
	v_lshlrev_b32_e32 v40, 16, v27
	v_and_b32_e32 v53, 0xffff0000, v28
	v_lshlrev_b32_e32 v52, 16, v28
	v_mul_f32_e32 v0, v53, v53
	v_lshlrev_b32_e32 v48, 16, v29
	v_and_b32_e32 v49, 0xffff0000, v29
	v_lshlrev_b32_e32 v64, 16, v35
	v_and_b32_e32 v65, 0xffff0000, v35
	v_lshlrev_b32_e32 v66, 16, v34
	v_and_b32_e32 v67, 0xffff0000, v34
	v_lshlrev_b32_e32 v34, 16, v33
	v_and_b32_e32 v35, 0xffff0000, v33
	v_lshlrev_b32_e32 v68, 16, v32
	v_and_b32_e32 v69, 0xffff0000, v32
	v_pk_fma_f32 v[32:33], v[52:53], v[52:53], v[0:1] op_sel_hi:[1,1,0]
	v_mul_f32_e32 v58, v49, v49
	v_pk_fma_f32 v[32:33], v[48:49], v[48:49], v[32:33]
	v_and_b32_e32 v41, 0xffff0000, v27
	v_lshlrev_b32_e32 v46, 16, v26
	v_and_b32_e32 v47, 0xffff0000, v26
	v_lshlrev_b32_e32 v26, 16, v30
	v_and_b32_e32 v27, 0xffff0000, v30
	v_pk_add_f32 v[32:33], v[58:59], v[32:33] op_sel_hi:[0,1]
	v_mul_f32_e32 v60, v27, v27
	v_pk_fma_f32 v[32:33], v[26:27], v[26:27], v[32:33]
	v_lshlrev_b32_e32 v44, 16, v31
	v_and_b32_e32 v45, 0xffff0000, v31
	v_pk_add_f32 v[32:33], v[60:61], v[32:33] op_sel_hi:[0,1]
	v_lshlrev_b32_e32 v30, 16, v25
	v_and_b32_e32 v31, 0xffff0000, v25
	v_and_b32_e32 v25, 0xffff0000, v24
	v_mul_f32_e32 v62, v45, v45
	v_pk_fma_f32 v[32:33], v[44:45], v[44:45], v[32:33]
	v_lshlrev_b32_e32 v50, 16, v24
	v_and_b32_e32 v24, s0, v24
	v_mov_b32_e32 v51, v25
	v_pk_add_f32 v[32:33], v[62:63], v[32:33] op_sel_hi:[0,1]
	v_pk_mul_f32 v[24:25], v[24:25], v[24:25]
	v_pk_mul_f32 v[76:77], v[68:69], v[68:69]
	v_pk_fma_f32 v[32:33], v[50:51], v[50:51], v[32:33]
	v_pk_mul_f32 v[56:57], v[30:31], v[30:31]
	v_pk_mul_f32 v[74:75], v[34:35], v[34:35]
	v_mov_b32_e32 v24, v76
	v_pk_mov_b32 v[32:33], v[76:77], v[32:33] op_sel:[1,0]
	v_mov_b32_e32 v79, v56
	v_mov_b32_e32 v78, v74
	v_pk_add_f32 v[24:25], v[24:25], v[32:33]
	v_pk_mul_f32 v[54:55], v[46:47], v[46:47]
	v_pk_mul_f32 v[72:73], v[66:67], v[66:67]
	v_mov_b32_e32 v56, v75
	v_pk_add_f32 v[24:25], v[78:79], v[24:25]
	v_mov_b32_e32 v81, v54
	v_mov_b32_e32 v80, v72
	v_pk_add_f32 v[24:25], v[56:57], v[24:25]
	v_pk_mul_f32 v[28:29], v[40:41], v[40:41]
	v_pk_mul_f32 v[70:71], v[64:65], v[64:65]
	v_mov_b32_e32 v54, v73
	v_pk_add_f32 v[24:25], v[80:81], v[24:25]
	v_mov_b32_e32 v83, v28
	v_mov_b32_e32 v82, v70
	v_pk_add_f32 v[24:25], v[54:55], v[24:25]
	v_mov_b32_e32 v28, v71
	v_pk_add_f32 v[24:25], v[82:83], v[24:25]
	s_nop 0
	v_pk_add_f32 v[24:25], v[28:29], v[24:25]
	ds_bpermute_b32 v29, v18, v25
	ds_bpermute_b32 v28, v18, v24
	s_waitcnt lgkmcnt(0)
	v_pk_add_f32 v[24:25], v[24:25], v[28:29]
	ds_bpermute_b32 v29, v19, v25
	ds_bpermute_b32 v28, v19, v24
	s_waitcnt lgkmcnt(0)
	v_pk_add_f32 v[24:25], v[24:25], v[28:29]
	ds_bpermute_b32 v29, v20, v25
	ds_bpermute_b32 v28, v20, v24
	s_waitcnt lgkmcnt(0)
	v_pk_add_f32 v[24:25], v[24:25], v[28:29]
	s_nop 0
	v_pk_fma_f32 v[24:25], v[24:25], s[4:5], v[14:15] op_sel_hi:[1,1,0]
	s_nop 0
	v_mul_f32_e32 v0, 0x4b800000, v25
	v_mul_f32_e32 v23, 0x4b800000, v24
	v_cmp_gt_f32_e32 vcc, s12, v24
	v_cmp_gt_f32_e64 s[6:7], s12, v25
	s_nop 0
	v_cndmask_b32_e32 v23, v24, v23, vcc
	v_cndmask_b32_e64 v0, v25, v0, s[6:7]
	v_rsq_f32_e32 v0, v0
	v_rsq_f32_e32 v23, v23
	v_mul_f32_e32 v24, 0x45800000, v0
	v_mul_f32_e32 v25, 0x45800000, v23
	v_cndmask_b32_e64 v0, v0, v24, s[6:7]
	v_cndmask_b32_e32 v24, v23, v25, vcc
	v_pk_mul_f32 v[28:29], v[0:1], v[52:53] op_sel_hi:[0,1]
	v_pk_mul_f32 v[32:33], v[0:1], v[50:51] op_sel_hi:[0,1]
	v_pk_mul_f32 v[48:49], v[0:1], v[48:49] op_sel_hi:[0,1]
	v_pk_mul_f32 v[30:31], v[0:1], v[30:31] op_sel_hi:[0,1]
	v_pk_mul_f32 v[26:27], v[0:1], v[26:27] op_sel_hi:[0,1]
	v_pk_mul_f32 v[46:47], v[0:1], v[46:47] op_sel_hi:[0,1]
	v_pk_mul_f32 v[44:45], v[0:1], v[44:45] op_sel_hi:[0,1]
	v_pk_mul_f32 v[40:41], v[0:1], v[40:41] op_sel_hi:[0,1]
	v_pk_mul_f32 v[50:51], v[24:25], v[68:69] op_sel_hi:[0,1]
	v_pk_mul_f32 v[34:35], v[24:25], v[34:35] op_sel_hi:[0,1]
	v_pk_mul_f32 v[52:53], v[24:25], v[66:67] op_sel_hi:[0,1]
	v_pk_mul_f32 v[54:55], v[24:25], v[64:65] op_sel_hi:[0,1]
	v_cvt_pk_bf16_f32 v24, v28, v29
	v_cvt_pk_bf16_f32 v28, v32, v33
	v_cvt_pk_bf16_f32 v25, v48, v49
	v_cvt_pk_bf16_f32 v29, v30, v31
	v_cvt_pk_bf16_f32 v26, v26, v27
	v_cvt_pk_bf16_f32 v30, v46, v47
	v_cvt_pk_bf16_f32 v27, v44, v45
	v_cvt_pk_bf16_f32 v31, v40, v41
	v_cvt_pk_bf16_f32 v32, v50, v51
	v_cvt_pk_bf16_f32 v33, v34, v35
	v_cvt_pk_bf16_f32 v34, v52, v53
	v_cvt_pk_bf16_f32 v35, v54, v55
	global_store_dwordx4 v[38:39], v[24:27], off
	global_store_dwordx4 v[38:39], v[28:31], off offset:16
	ds_write_b16 v22, v24
	ds_write_b16_d16_hi v22, v24 offset:144
	ds_write_b16 v22, v25 offset:288
	ds_write_b16_d16_hi v22, v25 offset:432
	ds_write_b16 v22, v26 offset:576
	ds_write_b16_d16_hi v22, v26 offset:720
	ds_write_b16 v22, v27 offset:864
	ds_write_b16_d16_hi v22, v27 offset:1008
	ds_write_b16 v22, v28 offset:1152
	ds_write_b16_d16_hi v22, v28 offset:1296
	ds_write_b16 v22, v29 offset:1440
	ds_write_b16_d16_hi v22, v29 offset:1584
	ds_write_b16 v22, v30 offset:1728
	ds_write_b16_d16_hi v22, v30 offset:1872
	ds_write_b16 v22, v31 offset:2016
	ds_write_b16_d16_hi v22, v31 offset:2160
	global_store_dwordx4 v[42:43], v[32:35], off
	s_waitcnt lgkmcnt(0)
	s_barrier
	ds_read_b128 v[24:27], v21
	ds_read_b128 v[28:31], v21 offset:16
	s_waitcnt lgkmcnt(1)
	global_store_dwordx4 v[36:37], v[24:27], off
	s_waitcnt lgkmcnt(0)
	global_store_dwordx4 v[36:37], v[28:31], off offset:16
	s_barrier
	s_cbranch_scc0 .LBB0_929

; #define LAS __attribute__((address_space(3)))
; #define GAS __attribute__((address_space(1)))
; __device__ __forceinline__ void indexer_unit(const Args& a, LAS unsigned char* lds, LAS unsigned long long* maskl, int b, int qblk, int wave, int lane) {
;     LAS float* sc = (LAS float*)lds;
;     const GAS bf16* z = (const GAS bf16*)(a.ws + WS_Z); const GAS bf16* ikn = (const GAS bf16*)(a.ws + WS_IKN);
;     const int fr = lane & 15, fq = lane >> 4, t0 = qblk * 16; const size_t rowb = (size_t)b * SEQ;
;     bf16x8 af[8][2]; float wv[8][4];
; #pragma unroll
;     for (int rt = 0; rt < 8; ++rt) {
;         const GAS bf16* p = z + (rowb + t0 + 2 * rt + (fr >> 3)) * ZW + ZIQ + (fr & 7) * 64 + 8 * fq;
;         af[rt][0] = __builtin_nontemporal_load((const GAS bf16x8*)p); af[rt][1] = __builtin_nontemporal_load((const GAS bf16x8*)(p + 32));
;         const u32x2 w = *(const GAS u32x2*)(z + (rowb + t0 + 2 * rt + (fq >> 1)) * ZW + ZIW + 4 * (fq & 1));
;         wv[rt][0] = bflo(w.x); wv[rt][1] = bfhi(w.x); wv[rt][2] = bflo(w.y); wv[rt][3] = bfhi(w.y);
;     }
;     const int nkt = qblk + 1;
;     bf16x8 nb0, nb1;
;     { const int k0 = wave < nkt ? wave : 0; const GAS bf16* p = ikn + (rowb + 16 * k0 + fr) * 64 + 8 * fq; nb0 = *(const GAS bf16x8*)p; nb1 = *(const GAS bf16x8*)(p + 32); }
;     for (int kt = wave; kt < nkt; kt += 8) {
;         const int key = 16 * kt + fr;
;         const bf16x8 b0 = nb0, b1 = nb1;
;         { const int k2 = kt + 8 < nkt ? kt + 8 : kt; const GAS bf16* p = ikn + (rowb + 16 * k2 + fr) * 64 + 8 * fq; nb0 = *(const GAS bf16x8*)p; nb1 = *(const GAS bf16x8*)(p + 32); }
.LBB0_1082:
	v_readlane_b32 s2, v254, 44
	v_mov_b32_e32 v76, v252
	s_or_b32 s9, s8, s2
	s_lshl_b32 s76, s9, 4
	v_and_b32_e32 v5, 63, v76
	v_readlane_b32 s2, v254, 4
	s_cmp_gt_u32 s2, s9
	v_lshlrev_b32_e32 v84, 6, v5
	s_cbranch_scc1 .Lhs_skip
	v_readlane_b32 s14, v254, 46
	v_readlane_b32 s4, v254, 24
	s_add_i32 s2, s76, s14
	v_bfe_u32 v57, v76, 3, 1
	v_readlane_b32 s5, v254, 25
	v_and_b32_e32 v2, 0x1c0, v84
	s_nop 0
	v_mov_b64_e32 v[46:47], s[4:5]
	s_movk_i32 s10, 0x1e00
	v_lshlrev_b32_e32 v48, 1, v2
	v_mov_b32_e32 v49, v4
	v_lshrrev_b32_e32 v119, 5, v5
	v_lshlrev_b32_e32 v74, 4, v5
	v_mov_b32_e32 v75, v4
	s_mov_b64 s[12:13], 0x1900
	s_or_b32 s3, s2, 2
	s_movk_i32 s11, 0x1000
	s_or_b32 s3, s2, 4
	s_or_b32 s3, s2, 6
	s_or_b32 s3, s2, 8
	s_or_b32 s3, s2, 10
	s_or_b32 s3, s2, 12
	v_or_b32_e32 v54, s3, v57
	v_mad_u64_u32 v[54:55], s[4:5], v54, s10, v[46:47]
	v_lshl_add_u64 v[54:55], v[54:55], 0, v[48:49]
	v_lshl_add_u64 v[54:55], v[54:55], 0, v[74:75]
	v_add_co_u32_e32 v56, vcc, s11, v54
	s_mov_b64 s[6:7], vcc
	s_or_b32 s4, s2, 14
	v_and_b32_e32 v77, 15, v76
	v_readlane_b32 s2, v254, 47
	s_nop 1
	v_mov_b32_e32 v66, s2
	v_mov_b32_e32 v67, v4
	v_readlane_b32 s2, v254, 26
	v_lshlrev_b64 v[66:67], 7, v[66:67]
	v_readlane_b32 s3, v254, 27
	s_nop 1
	v_lshl_add_u64 v[66:67], s[2:3], 0, v[66:67]
	v_lshl_add_u64 v[70:71], v[66:67], 0, v[74:75]
	v_cmp_lt_i32_e32 vcc, v227, v226
	global_load_dwordx4 v[66:69], v[70:71], off offset:1024
	global_load_dwordx4 v[70:73], v[70:71], off
	v_readlane_b32 s98, v254, 24
	v_readlane_b32 s99, v254, 25
	v_readlane_b32 s100, v254, 46
	v_bfe_u32 v86, v252, 3, 1
	v_lshrrev_b32_e32 v87, 5, v5
	v_and_b32_e32 v88, 7, v5
	s_add_i32 s100, s100, s76
	s_add_i32 s100, s100, s85
	v_and_b32_e32 v89, 48, v5
	v_lshl_or_b32 v88, v88, 7, v89
	v_or_b32_e32 v86, s100, v86
	v_or_b32_e32 v87, s100, v87
	s_movk_i32 s101, 0x1900
	s_movk_i32 s100, 0x1d90
	v_mul_u32_u24_e32 v86, 0x1e00, v86
	v_mul_u32_u24_e32 v87, 0x1e00, v87
	v_lshrrev_b32_e32 v89, 1, v5
	v_and_b32_e32 v89, 8, v89
	v_add3_u32 v86, v86, v88, s101
	v_add3_u32 v87, v87, v89, s100
	global_load_dwordx4 v[90:93], v86, s[98:99] nt
	global_load_dwordx4 v[94:97], v86, s[98:99] offset:64 nt
	global_load_dwordx2 v[98:99], v87, s[98:99]
	s_lshl_b32 s100, s85, 10
	s_lshl_b32 s101, s85, 8
	v_lshl_add_u32 v88, v5, 4, s100
	v_lshl_add_u32 v89, v5, 3, s101
	s_waitcnt vmcnt(0)
	ds_write_b128 v88, v[90:93]
	ds_write_b128 v88, v[94:97] offset:1024
	ds_write_b64 v89, v[98:99] offset:16384
	s_waitcnt lgkmcnt(0)
	s_barrier
	v_lshlrev_b32_e32 v88, 4, v5
	v_lshlrev_b32_e32 v89, 3, v5
	ds_read_b128 v[0:3], v88 offset:0
	ds_read_b128 v[6:9], v88 offset:1024
	ds_read_b128 v[14:17], v88 offset:2048
	ds_read_b128 v[10:13], v88 offset:3072
	ds_read_b128 v[18:21], v88 offset:4096
	ds_read_b128 v[22:25], v88 offset:5120
	ds_read_b128 v[30:33], v88 offset:6144
	ds_read_b128 v[26:29], v88 offset:7168
	ds_read_b128 v[34:37], v88 offset:8192
	ds_read_b128 v[38:41], v88 offset:9216
	ds_read_b128 v[42:45], v88 offset:10240
	ds_read_b128 v[50:53], v88 offset:11264
	ds_read_b128 v[54:57], v88 offset:12288
	ds_read_b128 v[58:61], v88 offset:13312
	ds_read_b128 v[46:49], v88 offset:14336
	ds_read_b128 v[62:65], v88 offset:15360
	ds_read_b64 v[78:79], v89 offset:16384
	ds_read_b64 v[80:81], v89 offset:16896
	ds_read_b64 v[82:83], v89 offset:17408
	ds_read_b64 v[100:101], v89 offset:17920
	ds_read_b64 v[104:105], v89 offset:18432
	ds_read_b64 v[108:109], v89 offset:18944
	ds_read_b64 v[112:113], v89 offset:19456
	ds_read_b64 v[116:117], v89 offset:19968
	s_waitcnt lgkmcnt(0)
	s_barrier
	s_waitcnt vmcnt(0)
	v_lshlrev_b32_e32 v93, 16, v82
	v_and_b32_e32 v94, 0xffff0000, v82
	v_lshlrev_b32_e32 v95, 16, v83
	v_and_b32_e32 v96, 0xffff0000, v83
	v_lshl_add_u64 v[82:83], s[2:3], 0, v[74:75]
	v_cndmask_b32_e32 v74, v253, v227, vcc
	v_lshlrev_b32_e32 v118, 2, v74
	v_and_b32_e32 v74, 16, v76
	v_cmp_eq_u32_e64 s[6:7], 0, v74
	v_lshlrev_b32_e32 v74, 2, v77
	v_lshl_or_b32 v74, v119, 13, v74
	v_readlane_b32 s2, v254, 36
	v_lshlrev_b32_e32 v85, 16, v78
	v_and_b32_e32 v86, 0xffff0000, v78
	v_lshlrev_b32_e32 v87, 16, v79
	v_and_b32_e32 v88, 0xffff0000, v79
	v_lshlrev_b32_e32 v89, 16, v80
	v_and_b32_e32 v90, 0xffff0000, v80
	v_lshlrev_b32_e32 v91, 16, v81
	v_and_b32_e32 v92, 0xffff0000, v81
	v_lshlrev_b32_e32 v97, 16, v100
	v_and_b32_e32 v98, 0xffff0000, v100
	v_lshlrev_b32_e32 v99, 16, v101
	v_and_b32_e32 v100, 0xffff0000, v101
	v_lshlrev_b32_e32 v101, 16, v104
	v_and_b32_e32 v102, 0xffff0000, v104
	v_lshlrev_b32_e32 v103, 16, v105
	v_and_b32_e32 v104, 0xffff0000, v105
	v_lshlrev_b32_e32 v105, 16, v108
	v_and_b32_e32 v106, 0xffff0000, v108
	v_lshlrev_b32_e32 v107, 16, v109
	v_and_b32_e32 v108, 0xffff0000, v109
	v_add_u32_e32 v119, s2, v74
	v_readlane_b32 s10, v254, 4
	v_lshlrev_b32_e32 v109, 16, v112
	v_and_b32_e32 v110, 0xffff0000, v112
	v_lshlrev_b32_e32 v111, 16, v113
	v_and_b32_e32 v112, 0xffff0000, v113
	v_lshlrev_b32_e32 v113, 16, v116
	v_and_b32_e32 v114, 0xffff0000, v116
	v_lshlrev_b32_e32 v115, 16, v117
	v_and_b32_e32 v116, 0xffff0000, v117
	v_mov_b32_e32 v117, s14
	s_branch .LBB0_1085

; #define GAS __attribute__((address_space(1)))
; __device__ __forceinline__ f32x4 mfma16(bf16x8 a, bf16x8 b, f32x4 c) { return __builtin_amdgcn_mfma_f32_16x16x32_bf16(a, b, c, 0, 0, 0); }
; __device__ __forceinline__ void indexer_unit(const Args& a, LAS unsigned char* lds, LAS unsigned long long* maskl, int b, int qblk, int wave, int lane) {
;     ...
;     for (int kt = wave; kt < nkt; kt += 8) {
;         const int key = 16 * kt + fr;
;         const bf16x8 b0 = nb0, b1 = nb1;
;         { const int k2 = kt + 8 < nkt ? kt + 8 : kt; const GAS bf16* p = ikn + (rowb + 16 * k2 + fr) * 64 + 8 * fq; nb0 = *(const GAS bf16x8*)p; nb1 = *(const GAS bf16x8*)(p + 32); }
; #pragma unroll
;         for (int rt = 0; rt < 8; ++rt) {
;             f32x4 acc = {0.f, 0.f, 0.f, 0.f};
;             __builtin_amdgcn_s_setprio(1); acc = mfma16(af[rt][0], b0, acc); acc = mfma16(af[rt][1], b1, acc); __builtin_amdgcn_s_setprio(0);
;             float part = wv[rt][0] * fmaxf(acc[0], 0.f) + wv[rt][1] * fmaxf(acc[1], 0.f) + wv[rt][2] * fmaxf(acc[2], 0.f) + wv[rt][3] * fmaxf(acc[3], 0.f);
;             part += __shfl_xor(part, 16); part += 0.f;
;             if ((fq & 1) == 0) sc[(2 * rt + (fq >> 1)) * 2048 + key] = part;
;         }
.LBB0_1085:
	s_mov_b32 s11, s10
	s_add_i32 s10, s10, 8
	s_cmp_gt_u32 s10, s9
	s_cselect_b64 s[2:3], -1, 0
	s_and_b64 s[4:5], s[2:3], exec
	s_cselect_b32 s4, s11, s10
	v_lshl_add_u32 v74, s4, 4, v117
	v_mov_b32_e32 v75, v4
	v_lshlrev_b64 v[74:75], 7, v[74:75]
	v_lshl_add_u64 v[78:79], v[82:83], 0, v[74:75]
	global_load_dwordx4 v[74:77], v[78:79], off
	s_nop 0
	global_load_dwordx4 v[78:81], v[78:79], off offset:1024
	s_setprio 1
	v_mfma_f32_16x16x32_bf16 v[128:131], v[0:3], v[70:73], 0
	v_mfma_f32_16x16x32_bf16 v[132:135], v[14:17], v[70:73], 0
	v_mfma_f32_16x16x32_bf16 v[136:139], v[18:21], v[70:73], 0
	v_mfma_f32_16x16x32_bf16 v[140:143], v[30:33], v[70:73], 0
	v_mfma_f32_16x16x32_bf16 v[144:147], v[34:37], v[70:73], 0
	v_mfma_f32_16x16x32_bf16 v[148:151], v[42:45], v[70:73], 0
	v_mfma_f32_16x16x32_bf16 v[152:155], v[54:57], v[70:73], 0
	v_mfma_f32_16x16x32_bf16 v[156:159], v[46:49], v[70:73], 0
	v_mfma_f32_16x16x32_bf16 v[128:131], v[6:9], v[66:69], v[128:131]
	v_mfma_f32_16x16x32_bf16 v[132:135], v[10:13], v[66:69], v[132:135]
	v_mfma_f32_16x16x32_bf16 v[136:139], v[22:25], v[66:69], v[136:139]
	v_mfma_f32_16x16x32_bf16 v[140:143], v[26:29], v[66:69], v[140:143]
	v_mfma_f32_16x16x32_bf16 v[144:147], v[38:41], v[66:69], v[144:147]
	v_mfma_f32_16x16x32_bf16 v[148:151], v[50:53], v[66:69], v[148:151]
	v_mfma_f32_16x16x32_bf16 v[152:155], v[58:61], v[66:69], v[152:155]
	v_mfma_f32_16x16x32_bf16 v[156:159], v[62:65], v[66:69], v[156:159]
	s_setprio 0
	s_nop 1
	v_max_f32_e32 v160, 0, v128
	v_max_f32_e32 v168, 0, v129
	v_fma_f32 v168, v168, v86, 0
	v_max_f32_e32 v161, 0, v130
	v_fmac_f32_e32 v168, v160, v85
	v_max_f32_e32 v160, 0, v131
	v_fmac_f32_e32 v168, v161, v87
	v_fmac_f32_e32 v168, v160, v88
	v_max_f32_e32 v160, 0, v132
	v_max_f32_e32 v169, 0, v133
	v_fma_f32 v169, v169, v90, 0
	v_max_f32_e32 v161, 0, v134
	v_fmac_f32_e32 v169, v160, v89
	v_max_f32_e32 v160, 0, v135
	v_fmac_f32_e32 v169, v161, v91
	v_fmac_f32_e32 v169, v160, v92
	v_max_f32_e32 v160, 0, v136
	v_max_f32_e32 v170, 0, v137
	v_fma_f32 v170, v170, v94, 0
	v_max_f32_e32 v161, 0, v138
	v_fmac_f32_e32 v170, v160, v93
	v_max_f32_e32 v160, 0, v139
	v_fmac_f32_e32 v170, v161, v95
	v_fmac_f32_e32 v170, v160, v96
	v_max_f32_e32 v160, 0, v140
	v_max_f32_e32 v171, 0, v141
	v_fma_f32 v171, v171, v98, 0
	v_max_f32_e32 v161, 0, v142
	v_fmac_f32_e32 v171, v160, v97
	v_max_f32_e32 v160, 0, v143
	v_fmac_f32_e32 v171, v161, v99
	v_fmac_f32_e32 v171, v160, v100
	v_max_f32_e32 v160, 0, v144
	v_max_f32_e32 v172, 0, v145
	v_fma_f32 v172, v172, v102, 0
	v_max_f32_e32 v161, 0, v146
	v_fmac_f32_e32 v172, v160, v101
	v_max_f32_e32 v160, 0, v147
	v_fmac_f32_e32 v172, v161, v103
	v_fmac_f32_e32 v172, v160, v104
	v_max_f32_e32 v160, 0, v148
	v_max_f32_e32 v173, 0, v149
	v_fma_f32 v173, v173, v106, 0
	v_max_f32_e32 v161, 0, v150
	v_fmac_f32_e32 v173, v160, v105
	v_max_f32_e32 v160, 0, v151
	v_fmac_f32_e32 v173, v161, v107
	v_fmac_f32_e32 v173, v160, v108
	v_max_f32_e32 v160, 0, v152
	v_max_f32_e32 v174, 0, v153
	v_fma_f32 v174, v174, v110, 0
	v_max_f32_e32 v161, 0, v154
	v_fmac_f32_e32 v174, v160, v109
	v_max_f32_e32 v160, 0, v155
	v_fmac_f32_e32 v174, v161, v111
	v_fmac_f32_e32 v174, v160, v112
	v_max_f32_e32 v160, 0, v156
	v_max_f32_e32 v175, 0, v157
	v_fma_f32 v175, v175, v114, 0
	v_max_f32_e32 v161, 0, v158
	v_fmac_f32_e32 v175, v160, v113
	v_max_f32_e32 v160, 0, v159
	v_fmac_f32_e32 v175, v161, v115
	v_fmac_f32_e32 v175, v160, v116
	s_nop 0
	v_permlane16_swap_b32_e32 v168, v172
	v_permlane16_swap_b32_e32 v169, v173
	v_permlane16_swap_b32_e32 v170, v174
	v_permlane16_swap_b32_e32 v171, v175
	v_add_f32_e32 v168, v168, v172
	v_add_f32_e32 v169, v169, v173
	v_add_f32_e32 v170, v170, v174
	v_add_f32_e32 v171, v171, v175
	v_and_b32_e32 v160, 16, v252
	v_lshl_add_u32 v160, v160, 12, v119
	ds_write_b32 v160, v168
	ds_write_b32 v160, v169 offset:16384
	ds_write_b32 v160, v170 offset:32768
	ds_write_b32 v160, v171 offset:49152
	s_branch .LBB0_1084
